# attention phase: waves 0-3 raised issue priority (s_setprio 3) so the two waves of a SIMD run a phase apart
# speedup vs baseline: 1.0018x; 1.0018x over previous
.LBB0_644:
	s_or_b64 exec, exec, s[0:1]
	s_mov_b64 s[6:7], 0
	s_mov_b64 s[4:5], 0
	s_mov_b64 s[0:1], 0
	s_mov_b64 s[8:9], 0
	v_mov_b32_e32 v2, v0
	s_cmpk_gt_i32 s86, 0x8ff
	s_waitcnt lgkmcnt(0)
	s_barrier
	s_cselect_b32 s99, 1, 0
	v_readfirstlane_b32 s98, v0
	s_bitcmp1_b32 s98, 8
	s_cbranch_scc1 .Lattn_prio_0
	s_setprio 3
.Lattn_prio_0:
	s_cmp_lg_u32 s99, 0
	s_cbranch_scc1 .LBB0_668
	v_readlane_b32 s12, v250, 0
	v_readlane_b32 s14, v250, 2
	v_readlane_b32 s15, v250, 3
	s_add_u32 s2, s14, s4
	s_addc_u32 s5, s15, s5
	s_add_u32 s4, s2, 0xd9e6000
	s_addc_u32 s5, s5, 0
	s_add_u32 s2, s14, s6
	s_addc_u32 s7, s15, s7
	s_add_u32 s6, s2, 0x145e6000
	s_addc_u32 s7, s7, 0
	s_add_u32 s10, s14, s8
	s_addc_u32 s11, s15, s9
	s_add_u32 s0, s14, s0
	v_lshlrev_b32_e32 v6, 4, v2
	s_addc_u32 s1, s15, s1
	v_mov_b32_e32 v115, 0
	v_and_b32_e32 v114, 0xf0, v6
	v_lshl_add_u64 v[6:7], s[0:1], 0, v[114:115]
	s_mov_b64 s[0:1], 0x121e6000
	v_lshl_add_u64 v[116:117], v[6:7], 0, s[0:1]
	v_lshl_add_u64 v[6:7], s[10:11], 0, v[114:115]
	s_mov_b64 s[0:1], 0x133e6000
	v_ashrrev_i32_e32 v1, 2, v2
	v_lshl_add_u64 v[118:119], v[6:7], 0, s[0:1]
	v_add_u32_e32 v6, 0x200, v2
	v_and_b32_e32 v3, 15, v2
	v_bfe_u32 v5, v2, 4, 2
	v_bfi_b32 v1, -16, v1, v2
	v_ashrrev_i32_e32 v167, 4, v2
	v_ashrrev_i32_e32 v168, 4, v6
	v_add_u32_e32 v6, 0x400, v2
	v_add_u32_e32 v2, 0x600, v2
	s_movk_i32 s1, 0x110
	v_lshlrev_b32_e32 v4, 3, v5
	v_cmp_eq_u32_e32 vcc, 0, v5
	v_ashrrev_i32_e32 v169, 4, v6
	v_ashrrev_i32_e32 v170, 4, v2
	v_add_u32_e32 v2, 0, v114
	s_movk_i32 s0, 0x120
	v_lshl_add_u32 v14, v5, 4, 0
	v_lshlrev_b32_e32 v114, 2, v5
	v_mad_u32_u24 v5, v3, s1, 0
	v_mul_u32_u24_e32 v16, 0x120, v3
	v_or_b32_e32 v3, 16, v3
	v_mul_lo_u32 v6, v167, s0
	v_mul_lo_u32 v7, v167, s1
	v_mul_lo_u32 v8, v168, s0
	v_mul_lo_u32 v9, v168, s1
	v_mul_lo_u32 v10, v169, s0
	v_mul_lo_u32 v11, v169, s1
	v_mul_lo_u32 v12, v170, s0
	v_mul_lo_u32 v13, v170, s1
	v_sub_u32_e32 v15, v14, v4
	v_mul_u32_u24_e32 v3, 0x110, v3
	s_mov_b32 s9, 0
	v_cndmask_b32_e64 v166, 0, 1.0, vcc
	v_sub_u32_e32 v171, 0x7f, v1
	v_lshlrev_b32_e32 v120, 1, v4
	v_mov_b32_e32 v121, v115
	s_mov_b32 s2, 0x9000
	v_add_u32_e32 v172, v2, v6
	v_add_u32_e32 v173, v2, v7
	v_add_u32_e32 v174, v2, v8
	v_add_u32_e32 v175, v2, v9
	v_add_u32_e32 v176, v2, v10
	v_add_u32_e32 v177, v2, v11
	v_add_u32_e32 v178, v2, v12
	v_add_u32_e32 v179, v2, v13
	v_add_u32_e32 v180, v14, v16
	s_mov_b32 s10, 0x3e0293ee
	v_add_u32_e32 v181, v5, v4
	v_add_u32_e32 v182, v15, v3
	s_mov_b32 s11, 0xc3e00000
	v_mbcnt_hi_u32_b32 v183, -1, v215
	v_mov_b32_e32 v184, 0x7f
	v_mov_b32_e32 v185, 0xff800000
	v_mov_b32_e32 v186, 0x43e00000
	s_mov_b32 s14, s86
	v_readlane_b32 s13, v250, 1
	s_branch .LBB0_647

.LBB0_668:
	s_setprio 0
	s_barrier
	s_waitcnt vmcnt(0)
	s_barrier
	s_and_saveexec_b64 s[0:1], s[78:79]
	s_cbranch_execz .LBB0_720
	s_add_i32 s2, 0, 0x20000
	v_mov_b32_e32 v1, s2
	s_waitcnt vmcnt(0) expcnt(0) lgkmcnt(0)
	ds_read_b32 v3, v1
	s_add_i32 s2, 0, 0x20004
	v_mov_b32_e32 v1, s2
	ds_read_b32 v1, v1
	s_waitcnt lgkmcnt(1)
	v_cmp_ne_u32_e32 vcc, 0, v3
	s_cbranch_vccnz .LBB0_684
	v_readlane_b32 s6, v250, 20
	v_readlane_b32 s7, v250, 21
	s_load_dword s2, s[6:7], 0x14
	s_load_dwordx2 s[4:5], s[6:7], 0x4
	s_mov_b32 s18, 1
	v_mov_b32_e32 v17, 0
	s_waitcnt lgkmcnt(0)
	s_lshr_b32 s8, s2, 16
	s_and_b32 s2, s2, 0xffff
	s_cmp_lg_u32 s2, 0
	s_cselect_b64 s[6:7], -1, 0
	s_cmp_lg_u64 s[6:7], 0
	s_addc_u32 s2, s4, 0
	s_cmp_lg_u32 s8, 0
	s_cselect_b64 s[6:7], -1, 0
	s_cmp_lg_u64 s[6:7], 0
	v_readlane_b32 s8, v250, 0
	s_mul_i32 s2, s2, s85
	s_addc_u32 s4, s5, 0
	v_readlane_b32 s10, v250, 2
	s_mul_i32 s2, s2, s4
	v_readlane_b32 s11, v250, 3
	s_add_u32 s4, s10, 0x1000
	s_addc_u32 s5, s11, 0
	s_add_u32 s6, s10, 0x1100
	s_addc_u32 s7, s11, 0
	v_readlane_b32 s9, v250, 1
	s_add_u32 s8, s10, 0x1200
	s_addc_u32 s9, s11, 0
	s_add_u32 s10, s10, 0x1300
	s_addc_u32 s11, s11, 0
	s_branch .LBB0_672

.LBB0_2547:
	s_or_b64 exec, exec, s[0:1]
	v_cndmask_b32_e64 v3, 0, 1, s[72:73]
	s_mov_b64 s[10:11], 0
	s_mov_b64 s[8:9], 0
	s_mov_b64 s[0:1], 0
	s_mov_b64 s[12:13], 0
	s_waitcnt lgkmcnt(0)
	v_mov_b32_e32 v2, v0
	v_cmp_ne_u32_e64 s[6:7], 1, v3
	s_andn2_b64 vcc, exec, s[72:73]
	s_barrier
	s_cselect_b32 s99, 1, 0
	v_readfirstlane_b32 s98, v0
	s_bitcmp1_b32 s98, 8
	s_cbranch_scc1 .Lattn_prio_1
	s_setprio 3
.Lattn_prio_1:
	s_cmp_lg_u32 s99, 0
	s_cbranch_vccnz .LBB0_2567
	v_readlane_b32 s16, v250, 0
	v_readlane_b32 s18, v250, 2
	v_readlane_b32 s19, v250, 3
	s_add_u32 s2, s18, s8
	s_addc_u32 s9, s19, s9
	s_add_u32 s8, s2, 0xd9e6000
	s_addc_u32 s9, s9, 0
	s_add_u32 s2, s18, s10
	s_addc_u32 s11, s19, s11
	s_add_u32 s10, s2, 0x145e6000
	s_addc_u32 s11, s11, 0
	s_add_u32 s14, s18, s12
	s_addc_u32 s15, s19, s13
	s_add_u32 s0, s18, s0
	v_lshlrev_b32_e32 v6, 4, v2
	s_addc_u32 s1, s19, s1
	v_mov_b32_e32 v115, 0
	v_and_b32_e32 v114, 0xf0, v6
	v_lshl_add_u64 v[6:7], s[0:1], 0, v[114:115]
	s_mov_b64 s[0:1], 0x121e6000
	v_lshl_add_u64 v[116:117], v[6:7], 0, s[0:1]
	v_lshl_add_u64 v[6:7], s[14:15], 0, v[114:115]
	s_mov_b64 s[0:1], 0x133e6000
	v_ashrrev_i32_e32 v4, 2, v2
	v_lshl_add_u64 v[118:119], v[6:7], 0, s[0:1]
	v_add_u32_e32 v6, 0x200, v2
	v_and_b32_e32 v3, 15, v2
	v_bfe_u32 v5, v2, 4, 2
	v_bfi_b32 v166, -16, v4, v2
	v_ashrrev_i32_e32 v168, 4, v2
	v_ashrrev_i32_e32 v169, 4, v6
	v_add_u32_e32 v6, 0x400, v2
	v_add_u32_e32 v2, 0x600, v2
	s_movk_i32 s1, 0x110
	v_lshlrev_b32_e32 v4, 3, v5
	v_cmp_eq_u32_e32 vcc, 0, v5
	v_ashrrev_i32_e32 v170, 4, v6
	v_ashrrev_i32_e32 v171, 4, v2
	v_add_u32_e32 v2, 0, v114
	s_movk_i32 s0, 0x120
	v_lshl_add_u32 v14, v5, 4, 0
	v_lshlrev_b32_e32 v114, 2, v5
	v_mad_u32_u24 v5, v3, s1, 0
	v_mul_u32_u24_e32 v16, 0x120, v3
	v_or_b32_e32 v3, 16, v3
	v_mul_lo_u32 v6, v168, s0
	v_mul_lo_u32 v7, v168, s1
	v_mul_lo_u32 v8, v169, s0
	v_mul_lo_u32 v9, v169, s1
	v_mul_lo_u32 v10, v170, s0
	v_mul_lo_u32 v11, v170, s1
	v_mul_lo_u32 v12, v171, s0
	v_mul_lo_u32 v13, v171, s1
	v_sub_u32_e32 v15, v14, v4
	v_mul_u32_u24_e32 v3, 0x110, v3
	s_mov_b32 s13, 0
	v_cndmask_b32_e64 v167, 0, 1.0, vcc
	v_sub_u32_e32 v172, 0x7f, v166
	v_lshlrev_b32_e32 v120, 1, v4
	v_mov_b32_e32 v121, v115
	s_mov_b32 s2, 0x9000
	v_add_u32_e32 v173, v2, v6
	v_add_u32_e32 v174, v2, v7
	v_add_u32_e32 v175, v2, v8
	v_add_u32_e32 v176, v2, v9
	v_add_u32_e32 v177, v2, v10
	v_add_u32_e32 v178, v2, v11
	v_add_u32_e32 v179, v2, v12
	v_add_u32_e32 v180, v2, v13
	v_add_u32_e32 v181, v14, v16
	s_mov_b32 s14, 0x3e0293ee
	v_add_u32_e32 v182, v5, v4
	v_add_u32_e32 v183, v15, v3
	s_mov_b32 s15, 0xc3e00000
	v_mov_b32_e32 v184, 0x7f
	v_mov_b32_e32 v185, 0xff800000
	v_mov_b32_e32 v186, 0x43e00000
	s_mov_b32 s18, s86
	v_readlane_b32 s17, v250, 1
	s_branch .LBB0_2550

.LBB0_2567:
	s_setprio 0
	s_barrier
	s_waitcnt vmcnt(0)
	s_barrier
	s_and_saveexec_b64 s[0:1], s[78:79]
	s_cbranch_execz .LBB0_2619
	s_add_i32 s2, 0, 0x20000
	v_mov_b32_e32 v2, s2
	s_waitcnt vmcnt(0) expcnt(0) lgkmcnt(0)
	ds_read_b32 v4, v2
	s_add_i32 s2, 0, 0x20004
	v_mov_b32_e32 v2, s2
	ds_read_b32 v2, v2
	s_waitcnt lgkmcnt(1)
	v_cmp_ne_u32_e32 vcc, 0, v4
	s_cbranch_vccnz .LBB0_2583
	v_readlane_b32 s10, v250, 20
	v_readlane_b32 s11, v250, 21
	s_load_dword s2, s[10:11], 0x14
	s_load_dwordx2 s[8:9], s[10:11], 0x4
	s_mov_b32 s22, 1
	v_mov_b32_e32 v18, 0
	s_waitcnt lgkmcnt(0)
	s_lshr_b32 s12, s2, 16
	s_and_b32 s2, s2, 0xffff
	s_cmp_lg_u32 s2, 0
	s_cselect_b64 s[10:11], -1, 0
	s_cmp_lg_u64 s[10:11], 0
	s_addc_u32 s2, s8, 0
	s_cmp_lg_u32 s12, 0
	s_cselect_b64 s[10:11], -1, 0
	s_cmp_lg_u64 s[10:11], 0
	v_readlane_b32 s12, v250, 0
	s_mul_i32 s2, s2, s85
	s_addc_u32 s8, s9, 0
	v_readlane_b32 s14, v250, 2
	s_mul_i32 s2, s2, s8
	v_readlane_b32 s15, v250, 3
	s_add_u32 s8, s14, 0x1000
	s_addc_u32 s9, s15, 0
	s_add_u32 s10, s14, 0x1100
	s_addc_u32 s11, s15, 0
	v_readlane_b32 s13, v250, 1
	s_add_u32 s12, s14, 0x1200
	s_addc_u32 s13, s15, 0
	s_add_u32 s14, s14, 0x1300
	s_addc_u32 s15, s15, 0
	s_branch .LBB0_2571
